# weight copies (f32 to bf16 transposed) rewritten: flat item list per phase, 16-byte loads, next item prefetched while the current one is transposed through LDS
# baseline (speedup 1.0000x reference)
; #define LAS __attribute__((address_space(3)))
; __device__ __forceinline__ const float* kin(int k) { KArgs p = (KArgs)__builtin_amdgcn_kernarg_segment_ptr(); asm volatile("" : "+s"(p)); return p->in[k]; }
; __device__ __forceinline__ void transpose_item(const float* W, const float* g, int ldw, int K, int ncols, bf16* WT, int mode, int roff, LAS float* scr, int item, int lane) {
;     const int nblk = ncols / 32, kb = item / nblk, nb = item % nblk, k0 = 64 * kb, n0 = 32 * nb;
; __global__ void __launch_bounds__(NWAVES * 64, 2) mk_fwd(Args args) {
;     ...
;         conv_w13(kin(6), kin(7), nullptr, ws, SCR_, F.lane, GW_, NGW);
;         conv_w2(kin(8), ws, SCR_, F.lane, (GW_ + NGW / 4) % NGW, NGW);
;         { const float* win = kin(10); bf16* WIN = (bf16*)(ws + WS_WIN);
;           conv_mat(win, nullptr, NIN, DM, 2560, WIN, 0, 0, SCR_, F.lane, (GW_ + NGW / 2) % NGW, NGW);
;           conv_mat(win + 2560, nullptr, NIN, DM, 512, WIN, 1, 2560, SCR_, F.lane, (GW_ + NGW / 8) % NGW, NGW);
;           conv_mat(win + 3072, nullptr, NIN, DM, 512, WIN, 1, 2560 + 16, SCR_, F.lane, (GW_ + 3 * (NGW / 8)) % NGW, NGW);
;           conv_mat(win + 3584, nullptr, NIN, DM, 2048, WIN, 0, 3584, SCR_, F.lane, (GW_ + 3 * (NGW / 4)) % NGW, NGW); }
.LBB0_13:
	s_or_b64 exec, exec, s[6:7]
	s_lshr_b32 s50, s3, 6
	s_add_u32 s30, s22, 0x2080000
	s_addc_u32 s31, s23, 0
	s_lshl_b32 s76, s18, 3
	s_bitcmp0_b32 s74, 0
	v_and_b32_e32 v189, 63, v0
	s_cbranch_scc1 .LBB0_63
	s_mov_b64 exec, -1
	v_readfirstlane_b32 s3, v0
	s_lshr_b32 s3, s3, 6
	s_lshl_b32 s12, s3, 14
	s_lshl_b32 s10, s33, 3
	s_add_i32 s10, s10, s3
	s_lshl_b32 s11, s18, 3
	v_and_b32_e32 v1, 63, v0
	v_lshrrev_b32_e32 v2, 3, v1
	v_and_b32_e32 v3, 7, v1
	v_lshlrev_b32_e32 v3, 4, v3
	v_mul_u32_u24_e32 v4, 0x84, v2
	v_add3_u32 v4, v4, v3, s12
	v_and_b32_e32 v5, 7, v1
	v_mul_u32_u24_e32 v5, 0x420, v5
	v_lshl_add_u32 v5, v2, 2, v5
	v_add_u32_e32 v5, s12, v5
	v_add_u32_e32 v6, 0, v2
	v_lshrrev_b32_e32 v10, 4, v6
	v_lshlrev_b32_e32 v10, 5, v10
	v_and_b32_e32 v14, 15, v6
	v_or_b32_e32 v10, v10, v14
	v_add_u32_e32 v7, 8, v2
	v_lshrrev_b32_e32 v11, 4, v7
	v_lshlrev_b32_e32 v11, 5, v11
	v_and_b32_e32 v14, 15, v7
	v_or_b32_e32 v11, v11, v14
	v_add_u32_e32 v8, 16, v2
	v_lshrrev_b32_e32 v12, 4, v8
	v_lshlrev_b32_e32 v12, 5, v12
	v_and_b32_e32 v14, 15, v8
	v_or_b32_e32 v12, v12, v14
	v_add_u32_e32 v9, 24, v2
	v_lshrrev_b32_e32 v13, 4, v9
	v_lshlrev_b32_e32 v13, 5, v13
	v_and_b32_e32 v14, 15, v9
	v_or_b32_e32 v13, v13, v14
	s_cmp_lt_u32 s10, 7040
	s_cbranch_scc0 .Lcw_p0_done
	s_cmp_lt_u32 s10, 1408
	s_cbranch_scc1 .Lcw_p0_i0_c0
	s_cmp_lt_u32 s10, 2816
	s_cbranch_scc1 .Lcw_p0_i0_c1
	s_cmp_lt_u32 s10, 4224
	s_cbranch_scc1 .Lcw_p0_i0_c2
	s_cmp_lt_u32 s10, 5504
	s_cbranch_scc1 .Lcw_p0_i0_c3
	s_cmp_lt_u32 s10, 5760
	s_cbranch_scc1 .Lcw_p0_i0_c4
	s_cmp_lt_u32 s10, 6016
	s_cbranch_scc1 .Lcw_p0_i0_c5
.Lcw_p0_i0_c6:
	s_load_dwordx2 s[8:9], s[0:1], 0x50
	s_sub_u32 s14, s10, 6016
	s_lshr_b32 s15, s14, 6
	s_and_b32 s16, s14, 63
	s_mul_i32 s17, s15, 0x160000
	s_lshl_b32 s19, s16, 7
	s_add_u32 s17, s17, s19
	s_add_u32 s17, s17, 0x3800
	s_mov_b32 s3, 0x5800
	s_mul_i32 s46, s16, 0x10000
	s_lshl_b32 s47, s15, 7
	s_add_u32 s46, s46, s47
	s_add_u32 s46, s46, 0x800000
	s_add_u32 s34, s22, s46
	s_addc_u32 s35, s23, 0
	s_mov_b32 s36, 0x800
	s_mov_b64 s[38:39], 0
	s_branch .Lcw_p0_i0_go
.Lcw_p0_i0_c5:
	s_load_dwordx2 s[8:9], s[0:1], 0x50
	s_sub_u32 s14, s10, 5760
	s_lshr_b32 s15, s14, 4
	s_and_b32 s16, s14, 15
	s_mul_i32 s17, s15, 0x160000
	s_lshl_b32 s19, s16, 7
	s_add_u32 s17, s17, s19
	s_add_u32 s17, s17, 0x3000
	s_mov_b32 s3, 0x5800
	s_mul_i32 s46, s16, 0x20000
	s_lshl_b32 s47, s15, 7
	s_add_u32 s46, s46, s47
	s_add_u32 s46, s46, 0x608000
	s_add_u32 s34, s22, s46
	s_addc_u32 s35, s23, 0
	s_mov_b32 s36, 0x800
	s_mov_b64 s[38:39], -1
	s_branch .Lcw_p0_i0_go
.Lcw_p0_i0_c4:
	s_load_dwordx2 s[8:9], s[0:1], 0x50
	s_sub_u32 s14, s10, 5504
	s_lshr_b32 s15, s14, 4
	s_and_b32 s16, s14, 15
	s_mul_i32 s17, s15, 0x160000
	s_lshl_b32 s19, s16, 7
	s_add_u32 s17, s17, s19
	s_add_u32 s17, s17, 0x2800
	s_mov_b32 s3, 0x5800
	s_mul_i32 s46, s16, 0x20000
	s_lshl_b32 s47, s15, 7
	s_add_u32 s46, s46, s47
	s_add_u32 s46, s46, 0x600000
	s_add_u32 s34, s22, s46
	s_addc_u32 s35, s23, 0
	s_mov_b32 s36, 0x800
	s_mov_b64 s[38:39], -1
	s_branch .Lcw_p0_i0_go
.Lcw_p0_i0_c3:
	s_load_dwordx2 s[8:9], s[0:1], 0x50
	s_sub_u32 s14, s10, 4224
	s_mul_hi_u32 s15, s14, 0x3333334
	s_mul_i32 s16, s15, 80
	s_sub_u32 s16, s14, s16
	s_mul_i32 s17, s15, 0x160000
	s_lshl_b32 s19, s16, 7
	s_add_u32 s17, s17, s19
	s_mov_b32 s3, 0x5800
	s_mul_i32 s46, s16, 0x10000
	s_lshl_b32 s47, s15, 7
	s_add_u32 s46, s46, s47
	s_add_u32 s46, s46, 0x100000
	s_add_u32 s34, s22, s46
	s_addc_u32 s35, s23, 0
	s_mov_b32 s36, 0x800
	s_mov_b64 s[38:39], 0
	s_branch .Lcw_p0_i0_go
.Lcw_p0_i0_c2:
	s_load_dwordx2 s[8:9], s[0:1], 0x40
	s_sub_u32 s14, s10, 2816
	s_lshr_b32 s15, s14, 5
	s_and_b32 s16, s14, 31
	s_mul_i32 s17, s15, 0x40000
	s_lshl_b32 s19, s16, 7
	s_add_u32 s17, s17, s19
	s_mov_b32 s3, 0x1000
	s_mul_i32 s46, s16, 0x2c000
	s_lshl_b32 s47, s15, 7
	s_add_u32 s46, s46, s47
	s_add_u32 s46, s46, 0x1b00000
	s_add_u32 s34, s22, s46
	s_addc_u32 s35, s23, 0
	s_mov_b32 s36, 0x1600
	s_mov_b64 s[38:39], 0
	s_branch .Lcw_p0_i0_go
.Lcw_p0_i0_c1:
	s_load_dwordx2 s[8:9], s[0:1], 0x38
	s_sub_u32 s14, s10, 1408
	s_mul_hi_u32 s15, s14, 0x2e8ba2f
	s_mul_i32 s16, s15, 88
	s_sub_u32 s16, s14, s16
	s_mul_i32 s17, s15, 0xb0000
	s_lshl_b32 s19, s16, 7
	s_add_u32 s17, s17, s19
	s_mov_b32 s3, 0x2c00
	s_mul_i32 s46, s16, 0x20000
	s_lshl_b32 s47, s15, 7
	s_add_u32 s46, s46, s47
	s_add_u32 s46, s46, 0x1008000
	s_add_u32 s34, s22, s46
	s_addc_u32 s35, s23, 0
	s_mov_b32 s36, 0x800
	s_mov_b64 s[38:39], -1
	s_branch .Lcw_p0_i0_go
.Lcw_p0_i0_c0:
	s_load_dwordx2 s[8:9], s[0:1], 0x30
	s_mov_b32 s14, s10
	s_mul_hi_u32 s15, s14, 0x2e8ba2f
	s_mul_i32 s16, s15, 88
	s_sub_u32 s16, s14, s16
	s_mul_i32 s17, s15, 0xb0000
	s_lshl_b32 s19, s16, 7
	s_add_u32 s17, s17, s19
	s_mov_b32 s3, 0x2c00
	s_mul_i32 s46, s16, 0x20000
	s_lshl_b32 s47, s15, 7
	s_add_u32 s46, s46, s47
	s_add_u32 s46, s46, 0x1000000
	s_add_u32 s34, s22, s46
	s_addc_u32 s35, s23, 0
	s_mov_b32 s36, 0x800
	s_mov_b64 s[38:39], -1
; #define LAS __attribute__((address_space(3)))
; __device__ __forceinline__ void transpose_item(const float* W, const float* g, int ldw, int K, int ncols, bf16* WT, int mode, int roff, LAS float* scr, int item, int lane) {
;     const int nblk = ncols / 32, kb = item / nblk, nb = item % nblk, k0 = 64 * kb, n0 = 32 * nb;
;     const float g0 = g ? g[k0 + lane] : 1.0f;
; #pragma unroll 8
;     for (int i = 0; i < 32; ++i) { const int kk = 2 * i + (lane >> 5); scr[kk * 33 + (lane & 31)] = W[(size_t)(k0 + kk) * ldw + n0 + (lane & 31)] * __shfl(g0, kk); }
.Lcw_p0_i0_go:
	s_waitcnt lgkmcnt(0)
	s_add_u32 s6, s8, s17
	s_addc_u32 s7, s9, 0
	v_mad_u32_u24 v14, v2, s3, v3
	s_lshl_b32 s3, s3, 3
	global_load_dwordx4 v[16:19], v14, s[6:7]
	s_add_u32 s6, s6, s3
	s_addc_u32 s7, s7, 0
	global_load_dwordx4 v[20:23], v14, s[6:7]
	s_add_u32 s6, s6, s3
	s_addc_u32 s7, s7, 0
	global_load_dwordx4 v[24:27], v14, s[6:7]
	s_add_u32 s6, s6, s3
	s_addc_u32 s7, s7, 0
	global_load_dwordx4 v[28:31], v14, s[6:7]
	s_add_u32 s6, s6, s3
	s_addc_u32 s7, s7, 0
	global_load_dwordx4 v[32:35], v14, s[6:7]
	s_add_u32 s6, s6, s3
	s_addc_u32 s7, s7, 0
	global_load_dwordx4 v[36:39], v14, s[6:7]
	s_add_u32 s6, s6, s3
	s_addc_u32 s7, s7, 0
	global_load_dwordx4 v[40:43], v14, s[6:7]
	s_add_u32 s6, s6, s3
	s_addc_u32 s7, s7, 0
	global_load_dwordx4 v[44:47], v14, s[6:7]
	s_mov_b32 s13, 1
.Lcw_p0_loop:
	s_add_u32 s10, s10, s11
	s_cmp_lt_u32 s10, 7040
	s_cbranch_scc0 .Lcw_p0_lastA
	s_cmp_lt_u32 s10, 1408
	s_cbranch_scc1 .Lcw_p0_i1_c0
	s_cmp_lt_u32 s10, 2816
	s_cbranch_scc1 .Lcw_p0_i1_c1
	s_cmp_lt_u32 s10, 4224
	s_cbranch_scc1 .Lcw_p0_i1_c2
	s_cmp_lt_u32 s10, 5504
	s_cbranch_scc1 .Lcw_p0_i1_c3
	s_cmp_lt_u32 s10, 5760
	s_cbranch_scc1 .Lcw_p0_i1_c4
	s_cmp_lt_u32 s10, 6016
	s_cbranch_scc1 .Lcw_p0_i1_c5
.Lcw_p0_i1_c6:
	s_load_dwordx2 s[8:9], s[0:1], 0x50
	s_sub_u32 s14, s10, 6016
	s_lshr_b32 s15, s14, 6
	s_and_b32 s16, s14, 63
	s_mul_i32 s17, s15, 0x160000
	s_lshl_b32 s19, s16, 7
	s_add_u32 s17, s17, s19
	s_add_u32 s17, s17, 0x3800
	s_mov_b32 s3, 0x5800
	s_mul_i32 s46, s16, 0x10000
	s_lshl_b32 s47, s15, 7
	s_add_u32 s46, s46, s47
	s_add_u32 s46, s46, 0x800000
	s_add_u32 s40, s22, s46
	s_addc_u32 s41, s23, 0
	s_mov_b32 s42, 0x800
	s_mov_b64 s[44:45], 0
	s_branch .Lcw_p0_i1_go
.Lcw_p0_i1_c5:
	s_load_dwordx2 s[8:9], s[0:1], 0x50
	s_sub_u32 s14, s10, 5760
	s_lshr_b32 s15, s14, 4
	s_and_b32 s16, s14, 15
	s_mul_i32 s17, s15, 0x160000
	s_lshl_b32 s19, s16, 7
	s_add_u32 s17, s17, s19
	s_add_u32 s17, s17, 0x3000
	s_mov_b32 s3, 0x5800
	s_mul_i32 s46, s16, 0x20000
	s_lshl_b32 s47, s15, 7
	s_add_u32 s46, s46, s47
	s_add_u32 s46, s46, 0x608000
	s_add_u32 s40, s22, s46
	s_addc_u32 s41, s23, 0
	s_mov_b32 s42, 0x800
	s_mov_b64 s[44:45], -1
	s_branch .Lcw_p0_i1_go
.Lcw_p0_i1_c4:
	s_load_dwordx2 s[8:9], s[0:1], 0x50
	s_sub_u32 s14, s10, 5504
	s_lshr_b32 s15, s14, 4
	s_and_b32 s16, s14, 15
	s_mul_i32 s17, s15, 0x160000
	s_lshl_b32 s19, s16, 7
	s_add_u32 s17, s17, s19
	s_add_u32 s17, s17, 0x2800
	s_mov_b32 s3, 0x5800
	s_mul_i32 s46, s16, 0x20000
	s_lshl_b32 s47, s15, 7
	s_add_u32 s46, s46, s47
	s_add_u32 s46, s46, 0x600000
	s_add_u32 s40, s22, s46
	s_addc_u32 s41, s23, 0
	s_mov_b32 s42, 0x800
	s_mov_b64 s[44:45], -1
	s_branch .Lcw_p0_i1_go
.Lcw_p0_i1_c3:
	s_load_dwordx2 s[8:9], s[0:1], 0x50
	s_sub_u32 s14, s10, 4224
	s_mul_hi_u32 s15, s14, 0x3333334
	s_mul_i32 s16, s15, 80
	s_sub_u32 s16, s14, s16
	s_mul_i32 s17, s15, 0x160000
	s_lshl_b32 s19, s16, 7
	s_add_u32 s17, s17, s19
	s_mov_b32 s3, 0x5800
	s_mul_i32 s46, s16, 0x10000
	s_lshl_b32 s47, s15, 7
	s_add_u32 s46, s46, s47
	s_add_u32 s46, s46, 0x100000
	s_add_u32 s40, s22, s46
	s_addc_u32 s41, s23, 0
	s_mov_b32 s42, 0x800
	s_mov_b64 s[44:45], 0
	s_branch .Lcw_p0_i1_go
.Lcw_p0_i1_c2:
	s_load_dwordx2 s[8:9], s[0:1], 0x40
	s_sub_u32 s14, s10, 2816
	s_lshr_b32 s15, s14, 5
	s_and_b32 s16, s14, 31
	s_mul_i32 s17, s15, 0x40000
	s_lshl_b32 s19, s16, 7
	s_add_u32 s17, s17, s19
	s_mov_b32 s3, 0x1000
	s_mul_i32 s46, s16, 0x2c000
	s_lshl_b32 s47, s15, 7
	s_add_u32 s46, s46, s47
	s_add_u32 s46, s46, 0x1b00000
	s_add_u32 s40, s22, s46
	s_addc_u32 s41, s23, 0
	s_mov_b32 s42, 0x1600
	s_mov_b64 s[44:45], 0
	s_branch .Lcw_p0_i1_go
.Lcw_p0_i1_c1:
	s_load_dwordx2 s[8:9], s[0:1], 0x38
	s_sub_u32 s14, s10, 1408
	s_mul_hi_u32 s15, s14, 0x2e8ba2f
	s_mul_i32 s16, s15, 88
	s_sub_u32 s16, s14, s16
	s_mul_i32 s17, s15, 0xb0000
	s_lshl_b32 s19, s16, 7
	s_add_u32 s17, s17, s19
	s_mov_b32 s3, 0x2c00
	s_mul_i32 s46, s16, 0x20000
	s_lshl_b32 s47, s15, 7
	s_add_u32 s46, s46, s47
	s_add_u32 s46, s46, 0x1008000
	s_add_u32 s40, s22, s46
	s_addc_u32 s41, s23, 0
	s_mov_b32 s42, 0x800
	s_mov_b64 s[44:45], -1
	s_branch .Lcw_p0_i1_go
.Lcw_p0_i1_c0:
	s_load_dwordx2 s[8:9], s[0:1], 0x30
	s_mov_b32 s14, s10
	s_mul_hi_u32 s15, s14, 0x2e8ba2f
	s_mul_i32 s16, s15, 88
	s_sub_u32 s16, s14, s16
	s_mul_i32 s17, s15, 0xb0000
	s_lshl_b32 s19, s16, 7
	s_add_u32 s17, s17, s19
	s_mov_b32 s3, 0x2c00
	s_mul_i32 s46, s16, 0x20000
	s_lshl_b32 s47, s15, 7
	s_add_u32 s46, s46, s47
	s_add_u32 s46, s46, 0x1000000
	s_add_u32 s40, s22, s46
	s_addc_u32 s41, s23, 0
	s_mov_b32 s42, 0x800
	s_mov_b64 s[44:45], -1
.Lcw_p0_i1_go:
	s_waitcnt lgkmcnt(0)
	s_add_u32 s6, s8, s17
	s_addc_u32 s7, s9, 0
	v_mad_u32_u24 v14, v2, s3, v3
	s_lshl_b32 s3, s3, 3
	global_load_dwordx4 v[48:51], v14, s[6:7]
	s_add_u32 s6, s6, s3
	s_addc_u32 s7, s7, 0
	global_load_dwordx4 v[52:55], v14, s[6:7]
	s_add_u32 s6, s6, s3
	s_addc_u32 s7, s7, 0
	global_load_dwordx4 v[56:59], v14, s[6:7]
	s_add_u32 s6, s6, s3
	s_addc_u32 s7, s7, 0
	global_load_dwordx4 v[60:63], v14, s[6:7]
	s_add_u32 s6, s6, s3
	s_addc_u32 s7, s7, 0
	global_load_dwordx4 v[64:67], v14, s[6:7]
	s_add_u32 s6, s6, s3
	s_addc_u32 s7, s7, 0
	global_load_dwordx4 v[68:71], v14, s[6:7]
	s_add_u32 s6, s6, s3
	s_addc_u32 s7, s7, 0
	global_load_dwordx4 v[72:75], v14, s[6:7]
	s_add_u32 s6, s6, s3
	s_addc_u32 s7, s7, 0
	global_load_dwordx4 v[76:79], v14, s[6:7]
	s_cmp_eq_u32 s13, 1
	s_cbranch_scc1 .Lcw_p0_w8
	s_waitcnt vmcnt(12)
	s_branch .Lcw_p0_pA

; #define GAS __attribute__((address_space(1)))
; #define LAS __attribute__((address_space(3)))
; #define LDS_WAIT() asm volatile("s_waitcnt lgkmcnt(0)" ::: "memory")
; __device__ __forceinline__ unsigned pk2(float lo, float hi) { const f32x2_t_ v = {lo, hi}; return __builtin_bit_cast(unsigned, __builtin_convertvector(v, bf16x2_t_)); }
; __device__ __forceinline__ void transpose_item(const float* W, const float* g, int ldw, int K, int ncols, bf16* WT, int mode, int roff, LAS float* scr, int item, int lane) {
;     ...
;     for (int i = 0; i < 32; ++i) { const int kk = 2 * i + (lane >> 5); scr[kk * 33 + (lane & 31)] = W[(size_t)(k0 + kk) * ldw + n0 + (lane & 31)] * __shfl(g0, kk); }
;     LDS_WAIT(); asm volatile("" ::: "memory");
;     const int c = lane & 7;
; #pragma unroll
;     for (int j = 0; j < 4; ++j) { const int n = (lane >> 3) + 8 * j; const LAS float* s = scr + (8 * c) * 33 + n;
;         v4u o; o.x = pk2(s[0 * 33], s[1 * 33]); o.y = pk2(s[2 * 33], s[3 * 33]); o.z = pk2(s[4 * 33], s[5 * 33]); o.w = pk2(s[6 * 33], s[7 * 33]);
;         const int jc = n0 + n; const int drow = mode ? roff + ((jc >> 4) << 5) + (jc & 15) : roff + jc;
;         *(GAS v4u*)(WT + (size_t)drow * K + k0 + 8 * c) = o; }
;     LDS_WAIT(); asm volatile("" ::: "memory");
.Lcw_p0_pA:
	s_mov_b32 s13, 0
	ds_write_b32 v4, v16
	ds_write_b32 v4, v17 offset:4
	ds_write_b32 v4, v18 offset:8
	ds_write_b32 v4, v19 offset:12
	ds_write_b32 v4, v20 offset:1056
	ds_write_b32 v4, v21 offset:1060
	ds_write_b32 v4, v22 offset:1064
	ds_write_b32 v4, v23 offset:1068
	ds_write_b32 v4, v24 offset:2112
	ds_write_b32 v4, v25 offset:2116
	ds_write_b32 v4, v26 offset:2120
	ds_write_b32 v4, v27 offset:2124
	ds_write_b32 v4, v28 offset:3168
	ds_write_b32 v4, v29 offset:3172
	ds_write_b32 v4, v30 offset:3176
	ds_write_b32 v4, v31 offset:3180
	ds_write_b32 v4, v32 offset:4224
	ds_write_b32 v4, v33 offset:4228
	ds_write_b32 v4, v34 offset:4232
	ds_write_b32 v4, v35 offset:4236
	ds_write_b32 v4, v36 offset:5280
	ds_write_b32 v4, v37 offset:5284
	ds_write_b32 v4, v38 offset:5288
	ds_write_b32 v4, v39 offset:5292
	ds_write_b32 v4, v40 offset:6336
	ds_write_b32 v4, v41 offset:6340
	ds_write_b32 v4, v42 offset:6344
	ds_write_b32 v4, v43 offset:6348
	ds_write_b32 v4, v44 offset:7392
	ds_write_b32 v4, v45 offset:7396
	ds_write_b32 v4, v46 offset:7400
	ds_write_b32 v4, v47 offset:7404
	v_cndmask_b32_e64 v15, v6, v10, s[38:39]
	v_mad_u32_u24 v128, v15, s36, v3
	v_cndmask_b32_e64 v15, v7, v11, s[38:39]
	v_mad_u32_u24 v129, v15, s36, v3
	v_cndmask_b32_e64 v15, v8, v12, s[38:39]
	v_mad_u32_u24 v130, v15, s36, v3
	v_cndmask_b32_e64 v15, v9, v13, s[38:39]
	v_mad_u32_u24 v131, v15, s36, v3
	s_waitcnt lgkmcnt(0)
	ds_read2_b32 v[80:81], v5 offset0:0 offset1:33
	ds_read2_b32 v[82:83], v5 offset0:66 offset1:99
	ds_read2_b32 v[84:85], v5 offset0:132 offset1:165
	ds_read2_b32 v[86:87], v5 offset0:198 offset1:231
	ds_read2_b32 v[88:89], v5 offset0:8 offset1:41
	ds_read2_b32 v[90:91], v5 offset0:74 offset1:107
	ds_read2_b32 v[92:93], v5 offset0:140 offset1:173
	ds_read2_b32 v[94:95], v5 offset0:206 offset1:239
	ds_read2_b32 v[96:97], v5 offset0:16 offset1:49
	ds_read2_b32 v[98:99], v5 offset0:82 offset1:115
	ds_read2_b32 v[100:101], v5 offset0:148 offset1:181
	ds_read2_b32 v[102:103], v5 offset0:214 offset1:247
	ds_read2_b32 v[104:105], v5 offset0:24 offset1:57
	ds_read2_b32 v[106:107], v5 offset0:90 offset1:123
	ds_read2_b32 v[108:109], v5 offset0:156 offset1:189
	ds_read2_b32 v[110:111], v5 offset0:222 offset1:255
	s_waitcnt lgkmcnt(12)
	v_cvt_pk_bf16_f32 v112, v80, v81
	v_cvt_pk_bf16_f32 v113, v82, v83
	v_cvt_pk_bf16_f32 v114, v84, v85
	v_cvt_pk_bf16_f32 v115, v86, v87
	global_store_dwordx4 v128, v[112:115], s[34:35]
	s_waitcnt lgkmcnt(8)
	v_cvt_pk_bf16_f32 v116, v88, v89
	v_cvt_pk_bf16_f32 v117, v90, v91
	v_cvt_pk_bf16_f32 v118, v92, v93
	v_cvt_pk_bf16_f32 v119, v94, v95
	global_store_dwordx4 v129, v[116:119], s[34:35]
	s_waitcnt lgkmcnt(4)
	v_cvt_pk_bf16_f32 v120, v96, v97
	v_cvt_pk_bf16_f32 v121, v98, v99
	v_cvt_pk_bf16_f32 v122, v100, v101
	v_cvt_pk_bf16_f32 v123, v102, v103
	global_store_dwordx4 v130, v[120:123], s[34:35]
	s_waitcnt lgkmcnt(0)
	v_cvt_pk_bf16_f32 v124, v104, v105
	v_cvt_pk_bf16_f32 v125, v106, v107
	v_cvt_pk_bf16_f32 v126, v108, v109
	v_cvt_pk_bf16_f32 v127, v110, v111
	global_store_dwordx4 v131, v[124:127], s[34:35]
	s_add_u32 s10, s10, s11
	s_cmp_lt_u32 s10, 7040
	s_cbranch_scc0 .Lcw_p0_lastB
	s_cmp_lt_u32 s10, 1408
	s_cbranch_scc1 .Lcw_p0_i2_c0
	s_cmp_lt_u32 s10, 2816
	s_cbranch_scc1 .Lcw_p0_i2_c1
	s_cmp_lt_u32 s10, 4224
	s_cbranch_scc1 .Lcw_p0_i2_c2
	s_cmp_lt_u32 s10, 5504
	s_cbranch_scc1 .Lcw_p0_i2_c3
	s_cmp_lt_u32 s10, 5760
	s_cbranch_scc1 .Lcw_p0_i2_c4
	s_cmp_lt_u32 s10, 6016
	s_cbranch_scc1 .Lcw_p0_i2_c5

; #define GAS __attribute__((address_space(1)))
; #define LAS __attribute__((address_space(3)))
; #define LDS_WAIT() asm volatile("s_waitcnt lgkmcnt(0)" ::: "memory")
; __device__ __forceinline__ unsigned pk2(float lo, float hi) { const f32x2_t_ v = {lo, hi}; return __builtin_bit_cast(unsigned, __builtin_convertvector(v, bf16x2_t_)); }
; __device__ __forceinline__ void transpose_item(const float* W, const float* g, int ldw, int K, int ncols, bf16* WT, int mode, int roff, LAS float* scr, int item, int lane) {
;     ...
; #pragma unroll 8
;     for (int i = 0; i < 32; ++i) { const int kk = 2 * i + (lane >> 5); scr[kk * 33 + (lane & 31)] = W[(size_t)(k0 + kk) * ldw + n0 + (lane & 31)] * __shfl(g0, kk); }
;     LDS_WAIT(); asm volatile("" ::: "memory");
;     const int c = lane & 7;
; #pragma unroll
;     for (int j = 0; j < 4; ++j) { const int n = (lane >> 3) + 8 * j; const LAS float* s = scr + (8 * c) * 33 + n;
;         v4u o; o.x = pk2(s[0 * 33], s[1 * 33]); o.y = pk2(s[2 * 33], s[3 * 33]); o.z = pk2(s[4 * 33], s[5 * 33]); o.w = pk2(s[6 * 33], s[7 * 33]);
;         const int jc = n0 + n; const int drow = mode ? roff + ((jc >> 4) << 5) + (jc & 15) : roff + jc;
;         *(GAS v4u*)(WT + (size_t)drow * K + k0 + 8 * c) = o; }
;     LDS_WAIT(); asm volatile("" ::: "memory");
.Lcw_p0_i2_go:
	s_waitcnt lgkmcnt(0)
	s_add_u32 s6, s8, s17
	s_addc_u32 s7, s9, 0
	v_mad_u32_u24 v14, v2, s3, v3
	s_lshl_b32 s3, s3, 3
	global_load_dwordx4 v[16:19], v14, s[6:7]
	s_add_u32 s6, s6, s3
	s_addc_u32 s7, s7, 0
	global_load_dwordx4 v[20:23], v14, s[6:7]
	s_add_u32 s6, s6, s3
	s_addc_u32 s7, s7, 0
	global_load_dwordx4 v[24:27], v14, s[6:7]
	s_add_u32 s6, s6, s3
	s_addc_u32 s7, s7, 0
	global_load_dwordx4 v[28:31], v14, s[6:7]
	s_add_u32 s6, s6, s3
	s_addc_u32 s7, s7, 0
	global_load_dwordx4 v[32:35], v14, s[6:7]
	s_add_u32 s6, s6, s3
	s_addc_u32 s7, s7, 0
	global_load_dwordx4 v[36:39], v14, s[6:7]
	s_add_u32 s6, s6, s3
	s_addc_u32 s7, s7, 0
	global_load_dwordx4 v[40:43], v14, s[6:7]
	s_add_u32 s6, s6, s3
	s_addc_u32 s7, s7, 0
	global_load_dwordx4 v[44:47], v14, s[6:7]
	s_waitcnt vmcnt(12)
	ds_write_b32 v4, v48
	ds_write_b32 v4, v49 offset:4
	ds_write_b32 v4, v50 offset:8
	ds_write_b32 v4, v51 offset:12
	ds_write_b32 v4, v52 offset:1056
	ds_write_b32 v4, v53 offset:1060
	ds_write_b32 v4, v54 offset:1064
	ds_write_b32 v4, v55 offset:1068
	ds_write_b32 v4, v56 offset:2112
	ds_write_b32 v4, v57 offset:2116
	ds_write_b32 v4, v58 offset:2120
	ds_write_b32 v4, v59 offset:2124
	ds_write_b32 v4, v60 offset:3168
	ds_write_b32 v4, v61 offset:3172
	ds_write_b32 v4, v62 offset:3176
	ds_write_b32 v4, v63 offset:3180
	ds_write_b32 v4, v64 offset:4224
	ds_write_b32 v4, v65 offset:4228
	ds_write_b32 v4, v66 offset:4232
	ds_write_b32 v4, v67 offset:4236
	ds_write_b32 v4, v68 offset:5280
	ds_write_b32 v4, v69 offset:5284
	ds_write_b32 v4, v70 offset:5288
	ds_write_b32 v4, v71 offset:5292
	ds_write_b32 v4, v72 offset:6336
	ds_write_b32 v4, v73 offset:6340
	ds_write_b32 v4, v74 offset:6344
	ds_write_b32 v4, v75 offset:6348
	ds_write_b32 v4, v76 offset:7392
	ds_write_b32 v4, v77 offset:7396
	ds_write_b32 v4, v78 offset:7400
	ds_write_b32 v4, v79 offset:7404
	v_cndmask_b32_e64 v15, v6, v10, s[44:45]
	v_mad_u32_u24 v128, v15, s42, v3
	v_cndmask_b32_e64 v15, v7, v11, s[44:45]
	v_mad_u32_u24 v129, v15, s42, v3
	v_cndmask_b32_e64 v15, v8, v12, s[44:45]
	v_mad_u32_u24 v130, v15, s42, v3
	v_cndmask_b32_e64 v15, v9, v13, s[44:45]
	v_mad_u32_u24 v131, v15, s42, v3
	s_waitcnt lgkmcnt(0)
	ds_read2_b32 v[80:81], v5 offset0:0 offset1:33
	ds_read2_b32 v[82:83], v5 offset0:66 offset1:99
	ds_read2_b32 v[84:85], v5 offset0:132 offset1:165
	ds_read2_b32 v[86:87], v5 offset0:198 offset1:231
	ds_read2_b32 v[88:89], v5 offset0:8 offset1:41
	ds_read2_b32 v[90:91], v5 offset0:74 offset1:107
	ds_read2_b32 v[92:93], v5 offset0:140 offset1:173
	ds_read2_b32 v[94:95], v5 offset0:206 offset1:239
	ds_read2_b32 v[96:97], v5 offset0:16 offset1:49
	ds_read2_b32 v[98:99], v5 offset0:82 offset1:115
	ds_read2_b32 v[100:101], v5 offset0:148 offset1:181
	ds_read2_b32 v[102:103], v5 offset0:214 offset1:247
	ds_read2_b32 v[104:105], v5 offset0:24 offset1:57
	ds_read2_b32 v[106:107], v5 offset0:90 offset1:123
	ds_read2_b32 v[108:109], v5 offset0:156 offset1:189
	ds_read2_b32 v[110:111], v5 offset0:222 offset1:255
	s_waitcnt lgkmcnt(12)
	v_cvt_pk_bf16_f32 v112, v80, v81
	v_cvt_pk_bf16_f32 v113, v82, v83
	v_cvt_pk_bf16_f32 v114, v84, v85
	v_cvt_pk_bf16_f32 v115, v86, v87
	global_store_dwordx4 v128, v[112:115], s[40:41]
	s_waitcnt lgkmcnt(8)
	v_cvt_pk_bf16_f32 v116, v88, v89
	v_cvt_pk_bf16_f32 v117, v90, v91
	v_cvt_pk_bf16_f32 v118, v92, v93
	v_cvt_pk_bf16_f32 v119, v94, v95
	global_store_dwordx4 v129, v[116:119], s[40:41]
	s_waitcnt lgkmcnt(4)
	v_cvt_pk_bf16_f32 v120, v96, v97
	v_cvt_pk_bf16_f32 v121, v98, v99
	v_cvt_pk_bf16_f32 v122, v100, v101
	v_cvt_pk_bf16_f32 v123, v102, v103
	global_store_dwordx4 v130, v[120:123], s[40:41]
	s_waitcnt lgkmcnt(0)
	v_cvt_pk_bf16_f32 v124, v104, v105
	v_cvt_pk_bf16_f32 v125, v106, v107
	v_cvt_pk_bf16_f32 v126, v108, v109
	v_cvt_pk_bf16_f32 v127, v110, v111
	global_store_dwordx4 v131, v[124:127], s[40:41]
	s_branch .Lcw_p0_loop
; #define GAS __attribute__((address_space(1)))
; #define LAS __attribute__((address_space(3)))
; #define LDS_WAIT() asm volatile("s_waitcnt lgkmcnt(0)" ::: "memory")
; __device__ __forceinline__ unsigned pk2(float lo, float hi) { const f32x2_t_ v = {lo, hi}; return __builtin_bit_cast(unsigned, __builtin_convertvector(v, bf16x2_t_)); }
; __device__ __forceinline__ void transpose_item(const float* W, const float* g, int ldw, int K, int ncols, bf16* WT, int mode, int roff, LAS float* scr, int item, int lane) {
;     ...
;     LDS_WAIT(); asm volatile("" ::: "memory");
;     const int c = lane & 7;
; #pragma unroll
;     for (int j = 0; j < 4; ++j) { const int n = (lane >> 3) + 8 * j; const LAS float* s = scr + (8 * c) * 33 + n;
;         v4u o; o.x = pk2(s[0 * 33], s[1 * 33]); o.y = pk2(s[2 * 33], s[3 * 33]); o.z = pk2(s[4 * 33], s[5 * 33]); o.w = pk2(s[6 * 33], s[7 * 33]);
;         const int jc = n0 + n; const int drow = mode ? roff + ((jc >> 4) << 5) + (jc & 15) : roff + jc;
;         *(GAS v4u*)(WT + (size_t)drow * K + k0 + 8 * c) = o; }
;     LDS_WAIT(); asm volatile("" ::: "memory");
.Lcw_p0_lastA:
	s_waitcnt vmcnt(0)
	ds_write_b32 v4, v16
	ds_write_b32 v4, v17 offset:4
	ds_write_b32 v4, v18 offset:8
	ds_write_b32 v4, v19 offset:12
	ds_write_b32 v4, v20 offset:1056
	ds_write_b32 v4, v21 offset:1060
	ds_write_b32 v4, v22 offset:1064
	ds_write_b32 v4, v23 offset:1068
	ds_write_b32 v4, v24 offset:2112
	ds_write_b32 v4, v25 offset:2116
	ds_write_b32 v4, v26 offset:2120
	ds_write_b32 v4, v27 offset:2124
	ds_write_b32 v4, v28 offset:3168
	ds_write_b32 v4, v29 offset:3172
	ds_write_b32 v4, v30 offset:3176
	ds_write_b32 v4, v31 offset:3180
	ds_write_b32 v4, v32 offset:4224
	ds_write_b32 v4, v33 offset:4228
	ds_write_b32 v4, v34 offset:4232
	ds_write_b32 v4, v35 offset:4236
	ds_write_b32 v4, v36 offset:5280
	ds_write_b32 v4, v37 offset:5284
	ds_write_b32 v4, v38 offset:5288
	ds_write_b32 v4, v39 offset:5292
	ds_write_b32 v4, v40 offset:6336
	ds_write_b32 v4, v41 offset:6340
	ds_write_b32 v4, v42 offset:6344
	ds_write_b32 v4, v43 offset:6348
	ds_write_b32 v4, v44 offset:7392
	ds_write_b32 v4, v45 offset:7396
	ds_write_b32 v4, v46 offset:7400
	ds_write_b32 v4, v47 offset:7404
	v_cndmask_b32_e64 v15, v6, v10, s[38:39]
	v_mad_u32_u24 v128, v15, s36, v3
	v_cndmask_b32_e64 v15, v7, v11, s[38:39]
	v_mad_u32_u24 v129, v15, s36, v3
	v_cndmask_b32_e64 v15, v8, v12, s[38:39]
	v_mad_u32_u24 v130, v15, s36, v3
	v_cndmask_b32_e64 v15, v9, v13, s[38:39]
	v_mad_u32_u24 v131, v15, s36, v3
	s_waitcnt lgkmcnt(0)
	ds_read2_b32 v[80:81], v5 offset0:0 offset1:33
	ds_read2_b32 v[82:83], v5 offset0:66 offset1:99
	ds_read2_b32 v[84:85], v5 offset0:132 offset1:165
	ds_read2_b32 v[86:87], v5 offset0:198 offset1:231
	ds_read2_b32 v[88:89], v5 offset0:8 offset1:41
	ds_read2_b32 v[90:91], v5 offset0:74 offset1:107
	ds_read2_b32 v[92:93], v5 offset0:140 offset1:173
	ds_read2_b32 v[94:95], v5 offset0:206 offset1:239
	ds_read2_b32 v[96:97], v5 offset0:16 offset1:49
	ds_read2_b32 v[98:99], v5 offset0:82 offset1:115
	ds_read2_b32 v[100:101], v5 offset0:148 offset1:181
	ds_read2_b32 v[102:103], v5 offset0:214 offset1:247
	ds_read2_b32 v[104:105], v5 offset0:24 offset1:57
	ds_read2_b32 v[106:107], v5 offset0:90 offset1:123
	ds_read2_b32 v[108:109], v5 offset0:156 offset1:189
	ds_read2_b32 v[110:111], v5 offset0:222 offset1:255
	s_waitcnt lgkmcnt(12)
	v_cvt_pk_bf16_f32 v112, v80, v81
	v_cvt_pk_bf16_f32 v113, v82, v83
	v_cvt_pk_bf16_f32 v114, v84, v85
	v_cvt_pk_bf16_f32 v115, v86, v87
	global_store_dwordx4 v128, v[112:115], s[34:35]
	s_waitcnt lgkmcnt(8)
	v_cvt_pk_bf16_f32 v116, v88, v89
	v_cvt_pk_bf16_f32 v117, v90, v91
	v_cvt_pk_bf16_f32 v118, v92, v93
	v_cvt_pk_bf16_f32 v119, v94, v95
	global_store_dwordx4 v129, v[116:119], s[34:35]
	s_waitcnt lgkmcnt(4)
	v_cvt_pk_bf16_f32 v120, v96, v97
	v_cvt_pk_bf16_f32 v121, v98, v99
	v_cvt_pk_bf16_f32 v122, v100, v101
	v_cvt_pk_bf16_f32 v123, v102, v103
	global_store_dwordx4 v130, v[120:123], s[34:35]
	s_waitcnt lgkmcnt(0)
	v_cvt_pk_bf16_f32 v124, v104, v105
	v_cvt_pk_bf16_f32 v125, v106, v107
	v_cvt_pk_bf16_f32 v126, v108, v109
	v_cvt_pk_bf16_f32 v127, v110, v111
	global_store_dwordx4 v131, v[124:127], s[34:35]
	s_branch .Lcw_p0_done
.Lcw_p0_lastB:
	s_waitcnt vmcnt(0)
	ds_write_b32 v4, v48
	ds_write_b32 v4, v49 offset:4
	ds_write_b32 v4, v50 offset:8
	ds_write_b32 v4, v51 offset:12
	ds_write_b32 v4, v52 offset:1056
	ds_write_b32 v4, v53 offset:1060
	ds_write_b32 v4, v54 offset:1064
	ds_write_b32 v4, v55 offset:1068
	ds_write_b32 v4, v56 offset:2112
	ds_write_b32 v4, v57 offset:2116
	ds_write_b32 v4, v58 offset:2120
	ds_write_b32 v4, v59 offset:2124
	ds_write_b32 v4, v60 offset:3168
	ds_write_b32 v4, v61 offset:3172
	ds_write_b32 v4, v62 offset:3176
	ds_write_b32 v4, v63 offset:3180
	ds_write_b32 v4, v64 offset:4224
	ds_write_b32 v4, v65 offset:4228
	ds_write_b32 v4, v66 offset:4232
	ds_write_b32 v4, v67 offset:4236
	ds_write_b32 v4, v68 offset:5280
	ds_write_b32 v4, v69 offset:5284
	ds_write_b32 v4, v70 offset:5288
	ds_write_b32 v4, v71 offset:5292
	ds_write_b32 v4, v72 offset:6336
	ds_write_b32 v4, v73 offset:6340
	ds_write_b32 v4, v74 offset:6344
	ds_write_b32 v4, v75 offset:6348
	ds_write_b32 v4, v76 offset:7392
	ds_write_b32 v4, v77 offset:7396
	ds_write_b32 v4, v78 offset:7400
	ds_write_b32 v4, v79 offset:7404
	v_cndmask_b32_e64 v15, v6, v10, s[44:45]
	v_mad_u32_u24 v128, v15, s42, v3
	v_cndmask_b32_e64 v15, v7, v11, s[44:45]
	v_mad_u32_u24 v129, v15, s42, v3
	v_cndmask_b32_e64 v15, v8, v12, s[44:45]
	v_mad_u32_u24 v130, v15, s42, v3
	v_cndmask_b32_e64 v15, v9, v13, s[44:45]
	v_mad_u32_u24 v131, v15, s42, v3
	s_waitcnt lgkmcnt(0)
	ds_read2_b32 v[80:81], v5 offset0:0 offset1:33
	ds_read2_b32 v[82:83], v5 offset0:66 offset1:99
	ds_read2_b32 v[84:85], v5 offset0:132 offset1:165
	ds_read2_b32 v[86:87], v5 offset0:198 offset1:231
	ds_read2_b32 v[88:89], v5 offset0:8 offset1:41
	ds_read2_b32 v[90:91], v5 offset0:74 offset1:107
	ds_read2_b32 v[92:93], v5 offset0:140 offset1:173
	ds_read2_b32 v[94:95], v5 offset0:206 offset1:239
	ds_read2_b32 v[96:97], v5 offset0:16 offset1:49
	ds_read2_b32 v[98:99], v5 offset0:82 offset1:115
	ds_read2_b32 v[100:101], v5 offset0:148 offset1:181
	ds_read2_b32 v[102:103], v5 offset0:214 offset1:247
	ds_read2_b32 v[104:105], v5 offset0:24 offset1:57
	ds_read2_b32 v[106:107], v5 offset0:90 offset1:123
	ds_read2_b32 v[108:109], v5 offset0:156 offset1:189
	ds_read2_b32 v[110:111], v5 offset0:222 offset1:255
	s_waitcnt lgkmcnt(12)
	v_cvt_pk_bf16_f32 v112, v80, v81
	v_cvt_pk_bf16_f32 v113, v82, v83
	v_cvt_pk_bf16_f32 v114, v84, v85
	v_cvt_pk_bf16_f32 v115, v86, v87
	global_store_dwordx4 v128, v[112:115], s[40:41]
	s_waitcnt lgkmcnt(8)
	v_cvt_pk_bf16_f32 v116, v88, v89
	v_cvt_pk_bf16_f32 v117, v90, v91
	v_cvt_pk_bf16_f32 v118, v92, v93
	v_cvt_pk_bf16_f32 v119, v94, v95
	global_store_dwordx4 v129, v[116:119], s[40:41]
	s_waitcnt lgkmcnt(4)
	v_cvt_pk_bf16_f32 v120, v96, v97
	v_cvt_pk_bf16_f32 v121, v98, v99
	v_cvt_pk_bf16_f32 v122, v100, v101
	v_cvt_pk_bf16_f32 v123, v102, v103
	global_store_dwordx4 v130, v[120:123], s[40:41]
	s_waitcnt lgkmcnt(0)
	v_cvt_pk_bf16_f32 v124, v104, v105
	v_cvt_pk_bf16_f32 v125, v106, v107
	v_cvt_pk_bf16_f32 v126, v108, v109
	v_cvt_pk_bf16_f32 v127, v110, v111
	global_store_dwordx4 v131, v[124:127], s[40:41]
.Lcw_p0_done:
	s_waitcnt lgkmcnt(0)
	v_and_b32_e32 v2, 31, v0

; #define LAS __attribute__((address_space(3)))
; __device__ __forceinline__ const float* kin(int k) { KArgs p = (KArgs)__builtin_amdgcn_kernarg_segment_ptr(); asm volatile("" : "+s"(p)); return p->in[k]; }
; __device__ __forceinline__ void transpose_item(const float* W, const float* g, int ldw, int K, int ncols, bf16* WT, int mode, int roff, LAS float* scr, int item, int lane) {
;     const int nblk = ncols / 32, kb = item / nblk, nb = item % nblk, k0 = 64 * kb, n0 = 32 * nb;
; __global__ void __launch_bounds__(NWAVES * 64, 2) mk_fwd(Args args) {
;     ...
;                 zb_rows(ws, kin(11), st_c, out, F.lane, cgw, CNGW);
;                 conv_mat(kin(13), nullptr, DM, DA, DM, (bf16*)(ws + WS_WA), 0, 0, SCR_, F.lane, cgw, CNGW);
;                 conv_mat(kin(14), nullptr, DM, DA, DM, (bf16*)(ws + WS_WB), 0, 0, SCR_, F.lane, (cgw + CNGW / 4) % CNGW, CNGW);
;                 conv_mat(kin(15), nullptr, DM, DM, DM, (bf16*)(ws + WS_WO), 0, 0, SCR_, F.lane, (cgw + CNGW / 2) % CNGW, CNGW);
;                 conv_w13(kin(17), kin(18), nullptr, ws, SCR_, F.lane, cgw, CNGW);
;                 conv_w2(kin(19), ws, SCR_, F.lane, (cgw + CNGW / 3) % CNGW, CNGW);
.LBB0_1163:
	s_or_b64 exec, exec, s[16:17]
	s_mov_b64 exec, -1
	v_readfirstlane_b32 s3, v0
	s_lshr_b32 s3, s3, 6
	s_lshl_b32 s12, s3, 14
	s_sub_i32 s10, s2, 0x80
	s_lshl_b32 s10, s10, 3
	s_add_i32 s10, s10, s3
	s_sub_i32 s11, s18, 0x80
	s_lshl_b32 s11, s11, 3
	v_and_b32_e32 v1, 63, v0
	v_lshrrev_b32_e32 v2, 3, v1
	v_and_b32_e32 v3, 7, v1
	v_lshlrev_b32_e32 v3, 4, v3
	v_mul_u32_u24_e32 v4, 0x84, v2
	v_add3_u32 v4, v4, v3, s12
	v_and_b32_e32 v5, 7, v1
	v_mul_u32_u24_e32 v5, 0x420, v5
	v_lshl_add_u32 v5, v2, 2, v5
	v_add_u32_e32 v5, s12, v5
	v_add_u32_e32 v6, 0, v2
	v_lshrrev_b32_e32 v10, 4, v6
	v_lshlrev_b32_e32 v10, 5, v10
	v_and_b32_e32 v14, 15, v6
	v_or_b32_e32 v10, v10, v14
	v_add_u32_e32 v7, 8, v2
	v_lshrrev_b32_e32 v11, 4, v7
	v_lshlrev_b32_e32 v11, 5, v11
	v_and_b32_e32 v14, 15, v7
	v_or_b32_e32 v11, v11, v14
	v_add_u32_e32 v8, 16, v2
	v_lshrrev_b32_e32 v12, 4, v8
	v_lshlrev_b32_e32 v12, 5, v12
	v_and_b32_e32 v14, 15, v8
	v_or_b32_e32 v12, v12, v14
	v_add_u32_e32 v9, 24, v2
	v_lshrrev_b32_e32 v13, 4, v9
	v_lshlrev_b32_e32 v13, 5, v13
	v_and_b32_e32 v14, 15, v9
	v_or_b32_e32 v13, v13, v14
	s_cmp_lt_u32 s10, 5248
	s_cbranch_scc0 .Lcw_p4b_done
	s_cmp_lt_u32 s10, 256
	s_cbranch_scc1 .Lcw_p4b_i0_c0
	s_cmp_lt_u32 s10, 512
	s_cbranch_scc1 .Lcw_p4b_i0_c1
	s_cmp_lt_u32 s10, 1024
	s_cbranch_scc1 .Lcw_p4b_i0_c2
	s_cmp_lt_u32 s10, 2432
	s_cbranch_scc1 .Lcw_p4b_i0_c3
	s_cmp_lt_u32 s10, 3840
	s_cbranch_scc1 .Lcw_p4b_i0_c4
.Lcw_p4b_i0_c5:
	s_load_dwordx2 s[8:9], s[0:1], 0x98
	s_sub_u32 s14, s10, 3840
	s_lshr_b32 s15, s14, 5
	s_and_b32 s16, s14, 31
	s_mul_i32 s17, s15, 0x40000
	s_lshl_b32 s19, s16, 7
	s_add_u32 s17, s17, s19
	s_mov_b32 s3, 0x1000
	s_mul_i32 s46, s16, 0x2c000
	s_lshl_b32 s47, s15, 7
	s_add_u32 s46, s46, s47
	s_add_u32 s46, s46, 0x1b00000
	s_add_u32 s34, s22, s46
	s_addc_u32 s35, s23, 0
	s_mov_b32 s36, 0x1600
	s_mov_b64 s[38:39], 0
	s_branch .Lcw_p4b_i0_go
.Lcw_p4b_i0_c4:
	s_load_dwordx2 s[8:9], s[0:1], 0x90
	s_sub_u32 s14, s10, 2432
	s_mul_hi_u32 s15, s14, 0x2e8ba2f
	s_mul_i32 s16, s15, 88
	s_sub_u32 s16, s14, s16
	s_mul_i32 s17, s15, 0xb0000
	s_lshl_b32 s19, s16, 7
	s_add_u32 s17, s17, s19
	s_mov_b32 s3, 0x2c00
	s_mul_i32 s46, s16, 0x20000
	s_lshl_b32 s47, s15, 7
	s_add_u32 s46, s46, s47
	s_add_u32 s46, s46, 0x1008000
	s_add_u32 s34, s22, s46
	s_addc_u32 s35, s23, 0
	s_mov_b32 s36, 0x800
	s_mov_b64 s[38:39], -1
	s_branch .Lcw_p4b_i0_go
.Lcw_p4b_i0_c3:
	s_load_dwordx2 s[8:9], s[0:1], 0x88
	s_sub_u32 s14, s10, 1024
	s_mul_hi_u32 s15, s14, 0x2e8ba2f
	s_mul_i32 s16, s15, 88
	s_sub_u32 s16, s14, s16
	s_mul_i32 s17, s15, 0xb0000
	s_lshl_b32 s19, s16, 7
	s_add_u32 s17, s17, s19
	s_mov_b32 s3, 0x2c00
	s_mul_i32 s46, s16, 0x20000
	s_lshl_b32 s47, s15, 7
	s_add_u32 s46, s46, s47
	s_add_u32 s46, s46, 0x1000000
	s_add_u32 s34, s22, s46
	s_addc_u32 s35, s23, 0
	s_mov_b32 s36, 0x800
	s_mov_b64 s[38:39], -1
	s_branch .Lcw_p4b_i0_go
.Lcw_p4b_i0_c2:
	s_load_dwordx2 s[8:9], s[0:1], 0x78
	s_sub_u32 s14, s10, 512
	s_lshr_b32 s15, s14, 5
	s_and_b32 s16, s14, 31
	s_mul_i32 s17, s15, 0x40000
	s_lshl_b32 s19, s16, 7
	s_add_u32 s17, s17, s19
	s_mov_b32 s3, 0x1000
	s_mul_i32 s46, s16, 0x10000
	s_lshl_b32 s47, s15, 7
	s_add_u32 s46, s46, s47
	s_add_u32 s46, s46, 0xe00000
	s_add_u32 s34, s22, s46
	s_addc_u32 s35, s23, 0
	s_mov_b32 s36, 0x800
	s_mov_b64 s[38:39], 0
	s_branch .Lcw_p4b_i0_go
.Lcw_p4b_i0_c1:
	s_load_dwordx2 s[8:9], s[0:1], 0x70
	s_sub_u32 s14, s10, 256
	s_lshr_b32 s15, s14, 5
	s_and_b32 s16, s14, 31
	s_mul_i32 s17, s15, 0x40000
	s_lshl_b32 s19, s16, 7
	s_add_u32 s17, s17, s19
	s_mov_b32 s3, 0x1000
	s_mul_i32 s46, s16, 0x8000
	s_lshl_b32 s47, s15, 7
	s_add_u32 s46, s46, s47
	s_add_u32 s46, s46, 0xd00000
	s_add_u32 s34, s22, s46
	s_addc_u32 s35, s23, 0
	s_mov_b32 s36, 0x400
	s_mov_b64 s[38:39], 0
	s_branch .Lcw_p4b_i0_go
.Lcw_p4b_i0_c0:
	s_load_dwordx2 s[8:9], s[0:1], 0x68
	s_mov_b32 s14, s10
	s_lshr_b32 s15, s14, 5
	s_and_b32 s16, s14, 31
	s_mul_i32 s17, s15, 0x40000
	s_lshl_b32 s19, s16, 7
	s_add_u32 s17, s17, s19
	s_mov_b32 s3, 0x1000
	s_mul_i32 s46, s16, 0x8000
	s_lshl_b32 s47, s15, 7
	s_add_u32 s46, s46, s47
	s_add_u32 s46, s46, 0xc00000
	s_add_u32 s34, s22, s46
	s_addc_u32 s35, s23, 0
	s_mov_b32 s36, 0x400
	s_mov_b64 s[38:39], 0

; #define LAS __attribute__((address_space(3)))
; __device__ __forceinline__ void conv_mat(const float* W, const float* g, int ldw, int K, int ncols, bf16* WT, int mode, int roff, LAS float* scr, int lane, int gw, int NGW) {
;     const int nitems = (K / 64) * (ncols / 32);
;     for (int it = gw; it < nitems; it += NGW) transpose_item(W, g, ldw, K, ncols, WT, mode, roff, scr, it, lane);
.Lcw_p4b_loop:
	s_add_u32 s10, s10, s11
	s_cmp_lt_u32 s10, 5248
	s_cbranch_scc0 .Lcw_p4b_lastA
	s_cmp_lt_u32 s10, 256
	s_cbranch_scc1 .Lcw_p4b_i1_c0
	s_cmp_lt_u32 s10, 512
	s_cbranch_scc1 .Lcw_p4b_i1_c1
	s_cmp_lt_u32 s10, 1024
	s_cbranch_scc1 .Lcw_p4b_i1_c2
	s_cmp_lt_u32 s10, 2432
	s_cbranch_scc1 .Lcw_p4b_i1_c3
	s_cmp_lt_u32 s10, 3840
	s_cbranch_scc1 .Lcw_p4b_i1_c4
.Lcw_p4b_i1_c5:
	s_load_dwordx2 s[8:9], s[0:1], 0x98
	s_sub_u32 s14, s10, 3840
	s_lshr_b32 s15, s14, 5
	s_and_b32 s16, s14, 31
	s_mul_i32 s17, s15, 0x40000
	s_lshl_b32 s19, s16, 7
	s_add_u32 s17, s17, s19
	s_mov_b32 s3, 0x1000
	s_mul_i32 s46, s16, 0x2c000
	s_lshl_b32 s47, s15, 7
	s_add_u32 s46, s46, s47
	s_add_u32 s46, s46, 0x1b00000
	s_add_u32 s40, s22, s46
	s_addc_u32 s41, s23, 0
	s_mov_b32 s42, 0x1600
	s_mov_b64 s[44:45], 0
	s_branch .Lcw_p4b_i1_go
.Lcw_p4b_i1_c4:
	s_load_dwordx2 s[8:9], s[0:1], 0x90
	s_sub_u32 s14, s10, 2432
	s_mul_hi_u32 s15, s14, 0x2e8ba2f
	s_mul_i32 s16, s15, 88
	s_sub_u32 s16, s14, s16
	s_mul_i32 s17, s15, 0xb0000
	s_lshl_b32 s19, s16, 7
	s_add_u32 s17, s17, s19
	s_mov_b32 s3, 0x2c00
	s_mul_i32 s46, s16, 0x20000
	s_lshl_b32 s47, s15, 7
	s_add_u32 s46, s46, s47
	s_add_u32 s46, s46, 0x1008000
	s_add_u32 s40, s22, s46
	s_addc_u32 s41, s23, 0
	s_mov_b32 s42, 0x800
	s_mov_b64 s[44:45], -1
	s_branch .Lcw_p4b_i1_go
.Lcw_p4b_i1_c3:
	s_load_dwordx2 s[8:9], s[0:1], 0x88
	s_sub_u32 s14, s10, 1024
	s_mul_hi_u32 s15, s14, 0x2e8ba2f
	s_mul_i32 s16, s15, 88
	s_sub_u32 s16, s14, s16
	s_mul_i32 s17, s15, 0xb0000
	s_lshl_b32 s19, s16, 7
	s_add_u32 s17, s17, s19
	s_mov_b32 s3, 0x2c00
	s_mul_i32 s46, s16, 0x20000
	s_lshl_b32 s47, s15, 7
	s_add_u32 s46, s46, s47
	s_add_u32 s46, s46, 0x1000000
	s_add_u32 s40, s22, s46
	s_addc_u32 s41, s23, 0
	s_mov_b32 s42, 0x800
	s_mov_b64 s[44:45], -1
	s_branch .Lcw_p4b_i1_go
.Lcw_p4b_i1_c2:
	s_load_dwordx2 s[8:9], s[0:1], 0x78
	s_sub_u32 s14, s10, 512
	s_lshr_b32 s15, s14, 5
	s_and_b32 s16, s14, 31
	s_mul_i32 s17, s15, 0x40000
	s_lshl_b32 s19, s16, 7
	s_add_u32 s17, s17, s19
	s_mov_b32 s3, 0x1000
	s_mul_i32 s46, s16, 0x10000
	s_lshl_b32 s47, s15, 7
	s_add_u32 s46, s46, s47
	s_add_u32 s46, s46, 0xe00000
	s_add_u32 s40, s22, s46
	s_addc_u32 s41, s23, 0
	s_mov_b32 s42, 0x800
	s_mov_b64 s[44:45], 0
	s_branch .Lcw_p4b_i1_go
.Lcw_p4b_i1_c1:
	s_load_dwordx2 s[8:9], s[0:1], 0x70
	s_sub_u32 s14, s10, 256
	s_lshr_b32 s15, s14, 5
	s_and_b32 s16, s14, 31
	s_mul_i32 s17, s15, 0x40000
	s_lshl_b32 s19, s16, 7
	s_add_u32 s17, s17, s19
	s_mov_b32 s3, 0x1000
	s_mul_i32 s46, s16, 0x8000
	s_lshl_b32 s47, s15, 7
	s_add_u32 s46, s46, s47
	s_add_u32 s46, s46, 0xd00000
	s_add_u32 s40, s22, s46
	s_addc_u32 s41, s23, 0
	s_mov_b32 s42, 0x400
	s_mov_b64 s[44:45], 0
	s_branch .Lcw_p4b_i1_go
.Lcw_p4b_i1_c0:
	s_load_dwordx2 s[8:9], s[0:1], 0x68
	s_mov_b32 s14, s10
	s_lshr_b32 s15, s14, 5
	s_and_b32 s16, s14, 31
	s_mul_i32 s17, s15, 0x40000
	s_lshl_b32 s19, s16, 7
	s_add_u32 s17, s17, s19
	s_mov_b32 s3, 0x1000
	s_mul_i32 s46, s16, 0x8000
	s_lshl_b32 s47, s15, 7
	s_add_u32 s46, s46, s47
	s_add_u32 s46, s46, 0xc00000
	s_add_u32 s40, s22, s46
	s_addc_u32 s41, s23, 0
	s_mov_b32 s42, 0x400
	s_mov_b64 s[44:45], 0

; #define GAS __attribute__((address_space(1)))
; #define LAS __attribute__((address_space(3)))
; #define LDS_WAIT() asm volatile("s_waitcnt lgkmcnt(0)" ::: "memory")
; __device__ __forceinline__ unsigned pk2(float lo, float hi) { const f32x2_t_ v = {lo, hi}; return __builtin_bit_cast(unsigned, __builtin_convertvector(v, bf16x2_t_)); }
; __device__ __forceinline__ void transpose_item(const float* W, const float* g, int ldw, int K, int ncols, bf16* WT, int mode, int roff, LAS float* scr, int item, int lane) {
;     ...
; #pragma unroll 8
;     for (int i = 0; i < 32; ++i) { const int kk = 2 * i + (lane >> 5); scr[kk * 33 + (lane & 31)] = W[(size_t)(k0 + kk) * ldw + n0 + (lane & 31)] * __shfl(g0, kk); }
;     LDS_WAIT(); asm volatile("" ::: "memory");
;     const int c = lane & 7;
; #pragma unroll
;     for (int j = 0; j < 4; ++j) { const int n = (lane >> 3) + 8 * j; const LAS float* s = scr + (8 * c) * 33 + n;
;         v4u o; o.x = pk2(s[0 * 33], s[1 * 33]); o.y = pk2(s[2 * 33], s[3 * 33]); o.z = pk2(s[4 * 33], s[5 * 33]); o.w = pk2(s[6 * 33], s[7 * 33]);
;         const int jc = n0 + n; const int drow = mode ? roff + ((jc >> 4) << 5) + (jc & 15) : roff + jc;
;         *(GAS v4u*)(WT + (size_t)drow * K + k0 + 8 * c) = o; }
;     LDS_WAIT(); asm volatile("" ::: "memory");
.Lcw_p4b_pA:
	s_mov_b32 s13, 0
	ds_write_b32 v4, v16
	ds_write_b32 v4, v17 offset:4
	ds_write_b32 v4, v18 offset:8
	ds_write_b32 v4, v19 offset:12
	ds_write_b32 v4, v20 offset:1056
	ds_write_b32 v4, v21 offset:1060
	ds_write_b32 v4, v22 offset:1064
	ds_write_b32 v4, v23 offset:1068
	ds_write_b32 v4, v24 offset:2112
	ds_write_b32 v4, v25 offset:2116
	ds_write_b32 v4, v26 offset:2120
	ds_write_b32 v4, v27 offset:2124
	ds_write_b32 v4, v28 offset:3168
	ds_write_b32 v4, v29 offset:3172
	ds_write_b32 v4, v30 offset:3176
	ds_write_b32 v4, v31 offset:3180
	ds_write_b32 v4, v32 offset:4224
	ds_write_b32 v4, v33 offset:4228
	ds_write_b32 v4, v34 offset:4232
	ds_write_b32 v4, v35 offset:4236
	ds_write_b32 v4, v36 offset:5280
	ds_write_b32 v4, v37 offset:5284
	ds_write_b32 v4, v38 offset:5288
	ds_write_b32 v4, v39 offset:5292
	ds_write_b32 v4, v40 offset:6336
	ds_write_b32 v4, v41 offset:6340
	ds_write_b32 v4, v42 offset:6344
	ds_write_b32 v4, v43 offset:6348
	ds_write_b32 v4, v44 offset:7392
	ds_write_b32 v4, v45 offset:7396
	ds_write_b32 v4, v46 offset:7400
	ds_write_b32 v4, v47 offset:7404
	v_cndmask_b32_e64 v15, v6, v10, s[38:39]
	v_mad_u32_u24 v128, v15, s36, v3
	v_cndmask_b32_e64 v15, v7, v11, s[38:39]
	v_mad_u32_u24 v129, v15, s36, v3
	v_cndmask_b32_e64 v15, v8, v12, s[38:39]
	v_mad_u32_u24 v130, v15, s36, v3
	v_cndmask_b32_e64 v15, v9, v13, s[38:39]
	v_mad_u32_u24 v131, v15, s36, v3
	s_waitcnt lgkmcnt(0)
	ds_read2_b32 v[80:81], v5 offset0:0 offset1:33
	ds_read2_b32 v[82:83], v5 offset0:66 offset1:99
	ds_read2_b32 v[84:85], v5 offset0:132 offset1:165
	ds_read2_b32 v[86:87], v5 offset0:198 offset1:231
	ds_read2_b32 v[88:89], v5 offset0:8 offset1:41
	ds_read2_b32 v[90:91], v5 offset0:74 offset1:107
	ds_read2_b32 v[92:93], v5 offset0:140 offset1:173
	ds_read2_b32 v[94:95], v5 offset0:206 offset1:239
	ds_read2_b32 v[96:97], v5 offset0:16 offset1:49
	ds_read2_b32 v[98:99], v5 offset0:82 offset1:115
	ds_read2_b32 v[100:101], v5 offset0:148 offset1:181
	ds_read2_b32 v[102:103], v5 offset0:214 offset1:247
	ds_read2_b32 v[104:105], v5 offset0:24 offset1:57
	ds_read2_b32 v[106:107], v5 offset0:90 offset1:123
	ds_read2_b32 v[108:109], v5 offset0:156 offset1:189
	ds_read2_b32 v[110:111], v5 offset0:222 offset1:255
	s_waitcnt lgkmcnt(12)
	v_cvt_pk_bf16_f32 v112, v80, v81
	v_cvt_pk_bf16_f32 v113, v82, v83
	v_cvt_pk_bf16_f32 v114, v84, v85
	v_cvt_pk_bf16_f32 v115, v86, v87
	global_store_dwordx4 v128, v[112:115], s[34:35]
	s_waitcnt lgkmcnt(8)
	v_cvt_pk_bf16_f32 v116, v88, v89
	v_cvt_pk_bf16_f32 v117, v90, v91
	v_cvt_pk_bf16_f32 v118, v92, v93
	v_cvt_pk_bf16_f32 v119, v94, v95
	global_store_dwordx4 v129, v[116:119], s[34:35]
	s_waitcnt lgkmcnt(4)
	v_cvt_pk_bf16_f32 v120, v96, v97
	v_cvt_pk_bf16_f32 v121, v98, v99
	v_cvt_pk_bf16_f32 v122, v100, v101
	v_cvt_pk_bf16_f32 v123, v102, v103
	global_store_dwordx4 v130, v[120:123], s[34:35]
	s_waitcnt lgkmcnt(0)
	v_cvt_pk_bf16_f32 v124, v104, v105
	v_cvt_pk_bf16_f32 v125, v106, v107
	v_cvt_pk_bf16_f32 v126, v108, v109
	v_cvt_pk_bf16_f32 v127, v110, v111
	global_store_dwordx4 v131, v[124:127], s[34:35]
	s_add_u32 s10, s10, s11
	s_cmp_lt_u32 s10, 5248
	s_cbranch_scc0 .Lcw_p4b_lastB
	s_cmp_lt_u32 s10, 256
	s_cbranch_scc1 .Lcw_p4b_i2_c0
	s_cmp_lt_u32 s10, 512
	s_cbranch_scc1 .Lcw_p4b_i2_c1
	s_cmp_lt_u32 s10, 1024
	s_cbranch_scc1 .Lcw_p4b_i2_c2
	s_cmp_lt_u32 s10, 2432
	s_cbranch_scc1 .Lcw_p4b_i2_c3
	s_cmp_lt_u32 s10, 3840
	s_cbranch_scc1 .Lcw_p4b_i2_c4

; #define GAS __attribute__((address_space(1)))
; #define LAS __attribute__((address_space(3)))
; #define LDS_WAIT() asm volatile("s_waitcnt lgkmcnt(0)" ::: "memory")
; __device__ __forceinline__ void transpose_item(const float* W, const float* g, int ldw, int K, int ncols, bf16* WT, int mode, int roff, LAS float* scr, int item, int lane) {
;     ...
;         *(GAS v4u*)(WT + (size_t)drow * K + k0 + 8 * c) = o; }
;     LDS_WAIT(); asm volatile("" ::: "memory");
; }
; __device__ __forceinline__ void conv_mat(const float* W, const float* g, int ldw, int K, int ncols, bf16* WT, int mode, int roff, LAS float* scr, int lane, int gw, int NGW) {
;     const int nitems = (K / 64) * (ncols / 32);
;     for (int it = gw; it < nitems; it += NGW) transpose_item(W, g, ldw, K, ncols, WT, mode, roff, scr, it, lane);
; }
.Lcw_p4b_done:
	s_waitcnt lgkmcnt(0)
.LBB0_1193:
	s_mov_b64 s[6:7], 0
